# software prefetch: first norm row loop issues one 64-lane touch load (one dword per 128-byte line) of the wave's next row ahead of the current row's loads
# speedup vs baseline: 1.0027x; 1.0027x over previous
; #define GAS __attribute__((address_space(1)))
; DI void phase_norm(const Ctx& C, const float* xlat, const float* xctx, bf16_t* H, const float* gn, const float* modl, int sh_off, int sc_off, int nrows, const float* part, int nsplit, float* xs_out) {
;     ...
;     for (int row = gw; row < nrows; row += NGW) {
;         const int b = row < NLAT ? (row >> 11) : 4;
;         const float* mb = modl + (size_t)b * MODW;
;         const GAS f32x4* xr = (const GAS f32x4*)(row < NLAT ? xlat + (size_t)row * DM : xctx + (size_t)(row - NLAT) * DM) + lane;
;         f32x4 v[8]; float s = 0.f;
; #pragma unroll
;         for (int j = 0; j < 8; ++j) v[j] = __builtin_nontemporal_load(xr + 64 * j);
.LBB0_155:
	s_add_i32 s98, s4, s10
	s_cmpk_gt_i32 s98, 0x1fff
	s_cbranch_scc1 .Lnpf_1
	s_add_u32 s98, s12, s14
	s_addc_u32 s99, s13, s15
	v_lshlrev_b32_e32 v70, 7, v206
	v_mov_b32_e32 v71, 0
	v_lshl_add_u64 v[70:71], v[70:71], 0, s[98:99]
	global_load_dword v72, v[70:71], off
